# chunk GEMM prologue: closed-form tile decode for the row-statistics table (256-workgroup grid)
# baseline (speedup 1.0000x reference)
.LBB0_917:
	s_mov_b32 s100, 0
	s_min_i32 s6, s14, 2
	s_lshl_b32 s53, s6, 1
	s_sub_i32 s61, 6, s53
	s_mov_b32 s28, 0
	s_and_b64 vcc, exec, s[4:5]
	s_cbranch_vccnz .LBB0_935
	s_lshl_b32 s22, s18, 8
	v_cmp_gt_i32_e32 vcc, s22, v2
	s_and_saveexec_b64 s[6:7], vcc
	s_cbranch_execz .LBB0_934
	v_and_b32_e32 v0, 15, v2
	s_waitcnt lgkmcnt(0)
	s_add_u32 s10, s8, 0x1000000
	v_subrev_co_u32_e32 v1, vcc, 4, v0
	v_cmp_gt_u32_e64 s[40:41], 12, v0
	s_addc_u32 s11, s9, 0
	s_lshl_b32 s14, -1, s61
	v_cndmask_b32_e64 v1, v0, v1, s[40:41]
	v_add_u32_e32 v4, 4, v0
	v_cmp_gt_u32_e64 s[40:41], 8, v0
	s_not_b32 s23, s14
	v_readlane_b32 s14, v253, 59
	v_cndmask_b32_e64 v1, v1, v4, s[40:41]
	v_and_b32_e32 v3, 0xff, v2
	v_cndmask_b32_e32 v4, v1, v0, vcc
	v_lshl_add_u32 v5, v2, 2, s14
	s_mov_b64 s[14:15], 0
	s_cmp_lg_u32 s52, 0x100
	s_cbranch_scc1 .LBB0_921
	s_cmp_eq_u32 s18, 6
	s_cbranch_scc1 .Lrt_fast
	s_cmp_eq_u32 s18, 4
	s_cbranch_scc0 .LBB0_921
.Lrt_fast:
	v_mov_b32_e32 v212, v5
	s_mov_b32 s100, 2
	s_cmp_eq_u32 s59, 8
	s_cselect_b32 s101, 6, 5
	v_and_b32_e32 v0, 0xffffff00, v2
	v_add_u32_e32 v0, s2, v0
	v_subrev_u32_e32 v1, s44, v0
	v_and_b32_e32 v6, 7, v0
	v_lshlrev_b32_e32 v6, 3, v6
	v_bfe_u32 v7, v0, 3, 3
	v_or_b32_e32 v7, v6, v7
	v_lshl_or_b32 v7, v7, 8, v3
	v_lshrrev_b32_e32 v8, s101, v1
	v_add_u32_e32 v8, v6, v8
	v_and_b32_e32 v9, s23, v8
	v_and_b32_e32 v1, 0xf0, v2
	v_lshl_or_b32 v9, v9, 8, v1
	v_add_u32_e32 v9, v4, v9
	v_lshrrev_b32_e32 v1, s61, v8
	v_lshl_add_u32 v9, v9, s53, v1
	v_cmp_gt_u32_e32 vcc, s44, v0
	s_nop 1
	v_cndmask_b32_e32 v0, v9, v7, vcc
	v_ashrrev_i32_e32 v1, 31, v0
	v_lshl_add_u64 v[0:1], v[0:1], 4, s[10:11]
	global_load_dwordx4 v[200:203], v[0:1], off
	v_add_u32_e32 v2, 0x200, v2
	v_and_b32_e32 v0, 0xffffff00, v2
	v_add_u32_e32 v0, s2, v0
	v_subrev_u32_e32 v1, s44, v0
	v_and_b32_e32 v6, 7, v0
	v_lshlrev_b32_e32 v6, 3, v6
	v_bfe_u32 v7, v0, 3, 3
	v_or_b32_e32 v7, v6, v7
	v_lshl_or_b32 v7, v7, 8, v3
	v_lshrrev_b32_e32 v8, s101, v1
	v_add_u32_e32 v8, v6, v8
	v_and_b32_e32 v9, s23, v8
	v_and_b32_e32 v1, 0xf0, v2
	v_lshl_or_b32 v9, v9, 8, v1
	v_add_u32_e32 v9, v4, v9
	v_lshrrev_b32_e32 v1, s61, v8
	v_lshl_add_u32 v9, v9, s53, v1
	v_cmp_gt_u32_e32 vcc, s44, v0
	s_nop 1
	v_cndmask_b32_e32 v0, v9, v7, vcc
	v_ashrrev_i32_e32 v1, 31, v0
	v_lshl_add_u64 v[0:1], v[0:1], 4, s[10:11]
	global_load_dwordx4 v[204:207], v[0:1], off
	v_add_u32_e32 v2, 0x200, v2
	s_cmp_eq_u32 s22, 0x400
	s_cbranch_scc1 .Lrt_issued
	v_and_b32_e32 v0, 0xffffff00, v2
	v_add_u32_e32 v0, s2, v0
	v_subrev_u32_e32 v1, s44, v0
	v_and_b32_e32 v6, 7, v0
	v_lshlrev_b32_e32 v6, 3, v6
	v_bfe_u32 v7, v0, 3, 3
	v_or_b32_e32 v7, v6, v7
	v_lshl_or_b32 v7, v7, 8, v3
	v_lshrrev_b32_e32 v8, s101, v1
	v_add_u32_e32 v8, v6, v8
	v_and_b32_e32 v9, s23, v8
	v_and_b32_e32 v1, 0xf0, v2
	v_lshl_or_b32 v9, v9, 8, v1
	v_add_u32_e32 v9, v4, v9
	v_lshrrev_b32_e32 v1, s61, v8
	v_lshl_add_u32 v9, v9, s53, v1
	v_cmp_gt_u32_e32 vcc, s44, v0
	s_nop 1
	v_cndmask_b32_e32 v0, v9, v7, vcc
	v_ashrrev_i32_e32 v1, 31, v0
	v_lshl_add_u64 v[0:1], v[0:1], 4, s[10:11]
	global_load_dwordx4 v[208:211], v[0:1], off
	v_add_u32_e32 v2, 0x200, v2
	s_mov_b32 s100, 3
